# P1 GEMM: first K iteration peeled with C=0 (rotating accumulators handled by dataflow), zeroing removed from P1 tile prologue; on top of v49
# speedup vs baseline: 1.0079x; 1.0018x over previous
.LBB0_443:
	s_andn2_b64 vcc, exec, s[58:59]
	s_waitcnt vmcnt(0)
	s_cbranch_vccnz .Lpz_zero_p1
	s_add_u32 s14, s4, 0x40080
	s_addc_u32 s15, s5, 0
	s_add_u32 s11, s70, 0x100
	s_addc_u32 s13, s71, 0
	s_mov_b32 s4, 0
	ds_read_b128 v[0:3], v190
	ds_read_b128 v[4:7], v190 offset:1024
	ds_read_b128 v[8:11], v190 offset:2048
	ds_read_b128 v[12:15], v190 offset:3072
	ds_read_b128 v[162:165], v191
	ds_read_b128 v[166:169], v191 offset:1024
	ds_read_b128 v[170:173], v191 offset:2048
	ds_read_b128 v[174:177], v191 offset:3072
	s_add_i32 s63, s4, 2
	s_add_u32 s5, s14, 0xfffc0080
	s_addc_u32 s65, s15, -1
	s_cmp_eq_u32 s96, s4
	s_cselect_b32 s4, s68, s11
	s_cselect_b32 s71, s67, s65
	s_cselect_b32 s70, s66, s5
	s_cselect_b32 s5, s69, s13
	v_lshl_add_u64 v[186:187], s[14:15], 0, v[156:157]
	s_add_i32 m0, s90, 0xc000
	ds_read_b128 v[178:181], v192
	ds_read_b128 v[182:185], v192 offset:1024
	ds_read_b128 v[196:199], v192 offset:2048
	ds_read_b128 v[200:203], v192 offset:3072
	ds_read_b128 v[204:207], v192 offset:4096
	ds_read_b128 v[208:211], v192 offset:5120
	ds_read_b128 v[212:215], v192 offset:6144
	ds_read_b128 v[216:219], v192 offset:7168
	global_load_lds_dwordx4 v[186:187], off
	v_lshl_add_u64 v[186:187], s[14:15], 0, v[158:159]
	s_add_i32 m0, s90, 0xe000
	s_nop 0
	global_load_lds_dwordx4 v[186:187], off
	s_waitcnt vmcnt(8)
	s_waitcnt lgkmcnt(0)
	s_barrier
	s_setprio 1
	s_waitcnt lgkmcnt(0)
	v_mfma_f32_16x16x32_bf16 v[16:19], v[0:3], v[178:181], 0
	v_mfma_f32_16x16x32_bf16 v[20:23], v[8:11], v[178:181], 0
	v_mfma_f32_16x16x32_bf16 v[128:131], v[0:3], v[196:199], 0
	v_mfma_f32_16x16x32_bf16 v[132:135], v[8:11], v[196:199], 0
	v_mfma_f32_16x16x32_bf16 v[112:115], v[0:3], v[204:207], 0
	v_mfma_f32_16x16x32_bf16 v[116:119], v[8:11], v[204:207], 0
	v_mfma_f32_16x16x32_bf16 v[96:99], v[0:3], v[212:215], 0
	v_mfma_f32_16x16x32_bf16 v[100:103], v[8:11], v[212:215], 0
	v_mfma_f32_16x16x32_bf16 v[16:19], v[4:7], v[182:185], v[16:19]
	v_mfma_f32_16x16x32_bf16 v[20:23], v[12:15], v[182:185], v[20:23]
	v_mfma_f32_16x16x32_bf16 v[128:131], v[4:7], v[200:203], v[128:131]
	v_mfma_f32_16x16x32_bf16 v[132:135], v[12:15], v[200:203], v[132:135]
	v_mfma_f32_16x16x32_bf16 v[112:115], v[4:7], v[208:211], v[112:115]
	v_mfma_f32_16x16x32_bf16 v[116:119], v[12:15], v[208:211], v[116:119]
	v_mfma_f32_16x16x32_bf16 v[96:99], v[4:7], v[216:219], v[96:99]
	v_mfma_f32_16x16x32_bf16 v[100:103], v[12:15], v[216:219], v[100:103]
	s_setprio 0
	s_setprio 1
	v_mfma_f32_16x16x32_bf16 v[24:27], v[162:165], v[178:181], 0
	v_mfma_f32_16x16x32_bf16 v[28:31], v[170:173], v[178:181], 0
	v_mfma_f32_16x16x32_bf16 v[136:139], v[162:165], v[196:199], 0
	v_mfma_f32_16x16x32_bf16 v[140:143], v[170:173], v[196:199], 0
	v_mfma_f32_16x16x32_bf16 v[120:123], v[162:165], v[204:207], 0
	v_mfma_f32_16x16x32_bf16 v[124:127], v[170:173], v[204:207], 0
	v_mfma_f32_16x16x32_bf16 v[104:107], v[162:165], v[212:215], 0
	v_mfma_f32_16x16x32_bf16 v[108:111], v[170:173], v[212:215], 0
	v_mfma_f32_16x16x32_bf16 v[24:27], v[166:169], v[182:185], v[24:27]
	v_mfma_f32_16x16x32_bf16 v[28:31], v[174:177], v[182:185], v[28:31]
	v_mfma_f32_16x16x32_bf16 v[136:139], v[166:169], v[200:203], v[136:139]
	v_mfma_f32_16x16x32_bf16 v[140:143], v[174:177], v[200:203], v[140:143]
	v_mfma_f32_16x16x32_bf16 v[120:123], v[166:169], v[208:211], v[120:123]
	v_mfma_f32_16x16x32_bf16 v[124:127], v[174:177], v[208:211], v[124:127]
	v_mfma_f32_16x16x32_bf16 v[104:107], v[166:169], v[216:219], v[104:107]
	v_mfma_f32_16x16x32_bf16 v[108:111], v[174:177], v[216:219], v[108:111]
	s_setprio 0
	s_barrier
	s_add_i32 s65, s38, s89
	v_lshl_add_u64 v[186:187], s[4:5], 0, v[144:145]
	s_mov_b32 m0, s65
	ds_read_b128 v[178:181], v192 offset:16384
	ds_read_b128 v[182:185], v192 offset:17408
	ds_read_b128 v[196:199], v192 offset:18432
	ds_read_b128 v[200:203], v192 offset:19456
	ds_read_b128 v[204:207], v192 offset:20480
	ds_read_b128 v[208:211], v192 offset:21504
	ds_read_b128 v[212:215], v192 offset:22528
	ds_read_b128 v[216:219], v192 offset:23552
	global_load_lds_dwordx4 v[186:187], off
	s_add_i32 m0, s65, 0x2000
	s_add_u32 s72, s4, 0x40000
	v_lshl_add_u64 v[220:221], s[4:5], 0, v[146:147]
	s_addc_u32 s73, s5, 0
	s_add_i32 s65, s39, s89
	global_load_lds_dwordx4 v[220:221], off
	v_lshl_add_u64 v[222:223], s[72:73], 0, v[144:145]
	s_mov_b32 m0, s65
	v_lshl_add_u64 v[224:225], s[70:71], 0, v[146:147]
	global_load_lds_dwordx4 v[222:223], off
	v_lshl_add_u64 v[222:223], s[72:73], 0, v[146:147]
	s_add_i32 m0, s65, 0x2000
	s_nop 0
	global_load_lds_dwordx4 v[222:223], off
	v_lshl_add_u64 v[222:223], s[70:71], 0, v[144:145]
	s_mov_b32 m0, s90
	s_nop 0
	global_load_lds_dwordx4 v[222:223], off
	s_mov_b32 m0, s91
	s_nop 0
	global_load_lds_dwordx4 v[224:225], off
	s_waitcnt vmcnt(8)
	s_waitcnt lgkmcnt(0)
	s_barrier
	s_setprio 1
	s_waitcnt lgkmcnt(0)
	v_mfma_f32_16x16x32_bf16 v[80:83], v[0:3], v[178:181], 0
	v_mfma_f32_16x16x32_bf16 v[84:87], v[8:11], v[178:181], 0
	v_mfma_f32_16x16x32_bf16 v[64:67], v[0:3], v[196:199], 0
	v_mfma_f32_16x16x32_bf16 v[68:71], v[8:11], v[196:199], 0
	v_mfma_f32_16x16x32_bf16 v[48:51], v[0:3], v[204:207], 0
	v_mfma_f32_16x16x32_bf16 v[52:55], v[8:11], v[204:207], 0
	v_mfma_f32_16x16x32_bf16 v[0:3], v[0:3], v[212:215], 0
	v_mfma_f32_16x16x32_bf16 v[80:83], v[4:7], v[182:185], v[80:83]
	v_mfma_f32_16x16x32_bf16 v[84:87], v[12:15], v[182:185], v[84:87]
	v_mfma_f32_16x16x32_bf16 v[64:67], v[4:7], v[200:203], v[64:67]
	v_mfma_f32_16x16x32_bf16 v[68:71], v[12:15], v[200:203], v[68:71]
	v_mfma_f32_16x16x32_bf16 v[48:51], v[4:7], v[208:211], v[48:51]
	v_mfma_f32_16x16x32_bf16 v[52:55], v[12:15], v[208:211], v[52:55]
	v_mfma_f32_16x16x32_bf16 v[0:3], v[4:7], v[216:219], v[0:3]
	v_mfma_f32_16x16x32_bf16 v[4:7], v[8:11], v[212:215], 0
	v_mfma_f32_16x16x32_bf16 v[4:7], v[12:15], v[216:219], v[4:7]
	s_setprio 0
	s_setprio 1
	v_mfma_f32_16x16x32_bf16 v[36:39], v[162:165], v[196:199], 0
	v_mfma_f32_16x16x32_bf16 v[72:75], v[166:169], v[200:203], v[36:39]
	v_mfma_f32_16x16x32_bf16 v[36:39], v[170:173], v[196:199], 0
	v_mfma_f32_16x16x32_bf16 v[76:79], v[174:177], v[200:203], v[36:39]
	v_mfma_f32_16x16x32_bf16 v[36:39], v[162:165], v[204:207], 0
	v_mfma_f32_16x16x32_bf16 v[56:59], v[166:169], v[208:211], v[36:39]
	v_mfma_f32_16x16x32_bf16 v[36:39], v[170:173], v[204:207], 0
	v_mfma_f32_16x16x32_bf16 v[60:63], v[174:177], v[208:211], v[36:39]
	v_mfma_f32_16x16x32_bf16 v[36:39], v[162:165], v[212:215], 0
	v_mfma_f32_16x16x32_bf16 v[32:35], v[170:173], v[212:215], 0
	v_mfma_f32_16x16x32_bf16 v[8:11], v[162:165], v[178:181], 0
	v_mfma_f32_16x16x32_bf16 v[12:15], v[170:173], v[178:181], 0
	v_mfma_f32_16x16x32_bf16 v[44:47], v[166:169], v[216:219], v[36:39]
	v_mfma_f32_16x16x32_bf16 v[32:35], v[174:177], v[216:219], v[32:35]
	v_mfma_f32_16x16x32_bf16 v[8:11], v[166:169], v[182:185], v[8:11]
	v_mfma_f32_16x16x32_bf16 v[12:15], v[174:177], v[182:185], v[12:15]
	s_setprio 0
	s_barrier
	s_add_i32 s65, 0, 0x18000
	s_add_i32 s72, 0, 0x1c000
	v_add_u32_e32 v92, s65, v189
	v_add_u32_e32 v150, s72, v189
	ds_read_b128 v[36:39], v92
	ds_read_b128 v[40:43], v92 offset:1024
	ds_read_b128 v[88:91], v92 offset:2048
	ds_read_b128 v[92:95], v92 offset:3072
	ds_read_b128 v[162:165], v150
	ds_read_b128 v[166:169], v150 offset:1024
	ds_read_b128 v[170:173], v150 offset:2048
	ds_read_b128 v[174:177], v150 offset:3072
	s_add_u32 s70, s70, 0x40000
	s_addc_u32 s71, s71, 0
	s_mov_b32 m0, s92
	v_lshl_add_u64 v[226:227], s[70:71], 0, v[144:145]
	ds_read_b128 v[178:181], v192 offset:32768
	ds_read_b128 v[182:185], v192 offset:33792
	ds_read_b128 v[196:199], v192 offset:34816
	ds_read_b128 v[200:203], v192 offset:35840
	ds_read_b128 v[204:207], v192 offset:36864
	ds_read_b128 v[208:211], v192 offset:37888
	ds_read_b128 v[212:215], v192 offset:38912
	ds_read_b128 v[216:219], v192 offset:39936
	global_load_lds_dwordx4 v[226:227], off
	v_lshl_add_u64 v[226:227], s[70:71], 0, v[146:147]
	s_mov_b32 m0, s93
	s_nop 0
	global_load_lds_dwordx4 v[226:227], off
	s_waitcnt vmcnt(8)
	s_waitcnt lgkmcnt(0)
	s_barrier
	s_setprio 1
	s_waitcnt lgkmcnt(0)
	v_mfma_f32_16x16x32_bf16 v[16:19], v[36:39], v[178:181], v[16:19]
	v_mfma_f32_16x16x32_bf16 v[20:23], v[88:91], v[178:181], v[20:23]
	v_mfma_f32_16x16x32_bf16 v[128:131], v[36:39], v[196:199], v[128:131]
	v_mfma_f32_16x16x32_bf16 v[132:135], v[88:91], v[196:199], v[132:135]
	v_mfma_f32_16x16x32_bf16 v[112:115], v[36:39], v[204:207], v[112:115]
	v_mfma_f32_16x16x32_bf16 v[116:119], v[88:91], v[204:207], v[116:119]
	v_mfma_f32_16x16x32_bf16 v[96:99], v[36:39], v[212:215], v[96:99]
	v_mfma_f32_16x16x32_bf16 v[100:103], v[88:91], v[212:215], v[100:103]
	v_mfma_f32_16x16x32_bf16 v[16:19], v[40:43], v[182:185], v[16:19]
	v_mfma_f32_16x16x32_bf16 v[20:23], v[92:95], v[182:185], v[20:23]
	v_mfma_f32_16x16x32_bf16 v[128:131], v[40:43], v[200:203], v[128:131]
	v_mfma_f32_16x16x32_bf16 v[132:135], v[92:95], v[200:203], v[132:135]
	v_mfma_f32_16x16x32_bf16 v[112:115], v[40:43], v[208:211], v[112:115]
	v_mfma_f32_16x16x32_bf16 v[116:119], v[92:95], v[208:211], v[116:119]
	v_mfma_f32_16x16x32_bf16 v[96:99], v[40:43], v[216:219], v[96:99]
	v_mfma_f32_16x16x32_bf16 v[100:103], v[92:95], v[216:219], v[100:103]
	s_setprio 0
	s_setprio 1
	v_mfma_f32_16x16x32_bf16 v[24:27], v[162:165], v[178:181], v[24:27]
	v_mfma_f32_16x16x32_bf16 v[28:31], v[170:173], v[178:181], v[28:31]
	v_mfma_f32_16x16x32_bf16 v[136:139], v[162:165], v[196:199], v[136:139]
	v_mfma_f32_16x16x32_bf16 v[140:143], v[170:173], v[196:199], v[140:143]
	v_mfma_f32_16x16x32_bf16 v[120:123], v[162:165], v[204:207], v[120:123]
	v_mfma_f32_16x16x32_bf16 v[124:127], v[170:173], v[204:207], v[124:127]
	v_mfma_f32_16x16x32_bf16 v[104:107], v[162:165], v[212:215], v[104:107]
	v_mfma_f32_16x16x32_bf16 v[108:111], v[170:173], v[212:215], v[108:111]
	v_mfma_f32_16x16x32_bf16 v[24:27], v[166:169], v[182:185], v[24:27]
	v_mfma_f32_16x16x32_bf16 v[28:31], v[174:177], v[182:185], v[28:31]
	v_mfma_f32_16x16x32_bf16 v[136:139], v[166:169], v[200:203], v[136:139]
	v_mfma_f32_16x16x32_bf16 v[140:143], v[174:177], v[200:203], v[140:143]
	v_mfma_f32_16x16x32_bf16 v[120:123], v[166:169], v[208:211], v[120:123]
	v_mfma_f32_16x16x32_bf16 v[124:127], v[174:177], v[208:211], v[124:127]
	v_mfma_f32_16x16x32_bf16 v[104:107], v[166:169], v[216:219], v[104:107]
	v_mfma_f32_16x16x32_bf16 v[108:111], v[174:177], v[216:219], v[108:111]
	s_setprio 0
	s_barrier
	s_add_i32 s65, s65, s89
	v_lshl_add_u64 v[186:187], v[186:187], 0, s[56:57]
	s_mov_b32 m0, s65
	ds_read_b128 v[178:181], v192 offset:49152
	ds_read_b128 v[182:185], v192 offset:50176
	ds_read_b128 v[196:199], v192 offset:51200
	ds_read_b128 v[200:203], v192 offset:52224
	ds_read_b128 v[204:207], v192 offset:53248
	ds_read_b128 v[208:211], v192 offset:54272
	ds_read_b128 v[212:215], v192 offset:55296
	ds_read_b128 v[216:219], v192 offset:56320
	global_load_lds_dwordx4 v[186:187], off
	s_add_i32 m0, s65, 0x2000
	s_add_u32 s4, s4, 0x40080
	v_lshl_add_u64 v[186:187], v[220:221], 0, s[56:57]
	s_addc_u32 s5, s5, 0
	s_add_i32 s65, s72, s89
	global_load_lds_dwordx4 v[186:187], off
	v_lshl_add_u64 v[186:187], s[4:5], 0, v[144:145]
	s_mov_b32 m0, s65
	s_nop 0
	global_load_lds_dwordx4 v[186:187], off
	v_lshl_add_u64 v[186:187], s[4:5], 0, v[146:147]
	s_add_i32 m0, s65, 0x2000
	s_nop 0
	global_load_lds_dwordx4 v[186:187], off
	v_lshl_add_u64 v[186:187], v[222:223], 0, s[56:57]
	s_mov_b32 m0, s81
	s_nop 0
	global_load_lds_dwordx4 v[186:187], off
	v_lshl_add_u64 v[186:187], v[224:225], 0, s[56:57]
	s_mov_b32 m0, s80
	s_nop 0
	global_load_lds_dwordx4 v[186:187], off
	s_waitcnt vmcnt(8)
	s_waitcnt lgkmcnt(0)
	s_barrier
	s_setprio 1
	s_waitcnt lgkmcnt(0)
	v_mfma_f32_16x16x32_bf16 v[0:3], v[36:39], v[212:215], v[0:3]
	v_mfma_f32_16x16x32_bf16 v[80:83], v[36:39], v[178:181], v[80:83]
	v_mfma_f32_16x16x32_bf16 v[84:87], v[88:91], v[178:181], v[84:87]
	v_mfma_f32_16x16x32_bf16 v[64:67], v[36:39], v[196:199], v[64:67]
	v_mfma_f32_16x16x32_bf16 v[68:71], v[88:91], v[196:199], v[68:71]
	v_mfma_f32_16x16x32_bf16 v[48:51], v[36:39], v[204:207], v[48:51]
	v_mfma_f32_16x16x32_bf16 v[52:55], v[88:91], v[204:207], v[52:55]
	v_mfma_f32_16x16x32_bf16 v[36:39], v[40:43], v[216:219], v[0:3]
	v_mfma_f32_16x16x32_bf16 v[0:3], v[88:91], v[212:215], v[4:7]
	v_mfma_f32_16x16x32_bf16 v[80:83], v[40:43], v[182:185], v[80:83]
	v_mfma_f32_16x16x32_bf16 v[84:87], v[92:95], v[182:185], v[84:87]
	v_mfma_f32_16x16x32_bf16 v[64:67], v[40:43], v[200:203], v[64:67]
	v_mfma_f32_16x16x32_bf16 v[68:71], v[92:95], v[200:203], v[68:71]
	v_mfma_f32_16x16x32_bf16 v[48:51], v[40:43], v[208:211], v[48:51]
	v_mfma_f32_16x16x32_bf16 v[52:55], v[92:95], v[208:211], v[52:55]
	v_mfma_f32_16x16x32_bf16 v[40:43], v[92:95], v[216:219], v[0:3]
	s_setprio 0
	s_setprio 1
	v_mfma_f32_16x16x32_bf16 v[0:3], v[162:165], v[178:181], v[8:11]
	v_mfma_f32_16x16x32_bf16 v[88:91], v[166:169], v[182:185], v[0:3]
	v_mfma_f32_16x16x32_bf16 v[0:3], v[170:173], v[178:181], v[12:15]
	v_mfma_f32_16x16x32_bf16 v[92:95], v[174:177], v[182:185], v[0:3]
	v_mfma_f32_16x16x32_bf16 v[0:3], v[162:165], v[196:199], v[72:75]
	v_mfma_f32_16x16x32_bf16 v[72:75], v[166:169], v[200:203], v[0:3]
	v_mfma_f32_16x16x32_bf16 v[0:3], v[170:173], v[196:199], v[76:79]
	v_mfma_f32_16x16x32_bf16 v[76:79], v[174:177], v[200:203], v[0:3]
	v_mfma_f32_16x16x32_bf16 v[0:3], v[162:165], v[204:207], v[56:59]
	v_mfma_f32_16x16x32_bf16 v[56:59], v[166:169], v[208:211], v[0:3]
	v_mfma_f32_16x16x32_bf16 v[0:3], v[170:173], v[204:207], v[60:63]
	v_mfma_f32_16x16x32_bf16 v[60:63], v[174:177], v[208:211], v[0:3]
	v_mfma_f32_16x16x32_bf16 v[0:3], v[162:165], v[212:215], v[44:47]
	v_mfma_f32_16x16x32_bf16 v[44:47], v[166:169], v[216:219], v[0:3]
	v_mfma_f32_16x16x32_bf16 v[0:3], v[170:173], v[212:215], v[32:35]
	v_mfma_f32_16x16x32_bf16 v[32:35], v[174:177], v[216:219], v[0:3]
	s_setprio 0
	s_barrier
	s_add_u32 s14, s14, 0x100
	s_addc_u32 s15, s15, 0
	s_add_u32 s11, s11, 0x100
	s_addc_u32 s13, s13, 0
	s_cmp_ge_i32 s63, s36
	s_mov_b32 s4, s63
	s_cbranch_scc0 .LBB0_445
	s_branch .LBB0_446
.Lpz_zero_p1:
	v_mov_b64_e32 v[18:19], 0
	v_mov_b64_e32 v[16:17], 0
	v_mov_b64_e32 v[22:23], 0
	v_mov_b64_e32 v[20:21], 0
	v_mov_b64_e32 v[130:131], 0
	v_mov_b64_e32 v[128:129], 0
	v_mov_b64_e32 v[134:135], 0
	v_mov_b64_e32 v[132:133], 0
	v_mov_b64_e32 v[114:115], 0
	v_mov_b64_e32 v[112:113], 0
	v_mov_b64_e32 v[118:119], 0
	v_mov_b64_e32 v[116:117], 0
	v_mov_b64_e32 v[98:99], 0
	v_mov_b64_e32 v[96:97], 0
	v_mov_b64_e32 v[102:103], 0
	v_mov_b64_e32 v[100:101], 0
	v_mov_b64_e32 v[26:27], 0
	v_mov_b64_e32 v[24:25], 0
	v_mov_b64_e32 v[30:31], 0
	v_mov_b64_e32 v[28:29], 0
	v_mov_b64_e32 v[138:139], 0
	v_mov_b64_e32 v[136:137], 0
	v_mov_b64_e32 v[142:143], 0
	v_mov_b64_e32 v[140:141], 0
	v_mov_b64_e32 v[122:123], 0
	v_mov_b64_e32 v[120:121], 0
	v_mov_b64_e32 v[126:127], 0
	v_mov_b64_e32 v[124:125], 0
	v_mov_b64_e32 v[106:107], 0
	v_mov_b64_e32 v[104:105], 0
	v_mov_b64_e32 v[110:111], 0
	v_mov_b64_e32 v[108:109], 0
	v_mov_b64_e32 v[82:83], 0
	v_mov_b64_e32 v[80:81], 0
	v_mov_b64_e32 v[86:87], 0
	v_mov_b64_e32 v[84:85], 0
	v_mov_b64_e32 v[66:67], 0
	v_mov_b64_e32 v[64:65], 0
	v_mov_b64_e32 v[70:71], 0
	v_mov_b64_e32 v[68:69], 0
	v_mov_b64_e32 v[50:51], 0
	v_mov_b64_e32 v[48:49], 0
	v_mov_b64_e32 v[54:55], 0
	v_mov_b64_e32 v[52:53], 0
	v_mov_b64_e32 v[38:39], 0
	v_mov_b64_e32 v[36:37], 0
	v_mov_b64_e32 v[42:43], 0
	v_mov_b64_e32 v[40:41], 0
	v_mov_b64_e32 v[90:91], 0
	v_mov_b64_e32 v[88:89], 0
	v_mov_b64_e32 v[94:95], 0
	v_mov_b64_e32 v[92:93], 0
	v_mov_b64_e32 v[74:75], 0
	v_mov_b64_e32 v[72:73], 0
	v_mov_b64_e32 v[78:79], 0
	v_mov_b64_e32 v[76:77], 0
	v_mov_b64_e32 v[58:59], 0
	v_mov_b64_e32 v[56:57], 0
	v_mov_b64_e32 v[62:63], 0
	v_mov_b64_e32 v[60:61], 0
	v_mov_b64_e32 v[46:47], 0
	v_mov_b64_e32 v[44:45], 0
	v_mov_b64_e32 v[34:35], 0
	v_mov_b64_e32 v[32:33], 0
	s_branch .LBB0_446
